# plus: qkv tiles dealt in reverse workgroup order to balance against the conv tiles
# baseline (speedup 1.0000x reference)
; DEVI int tid_opaque() { int t = threadIdx.x; asm volatile("" : "+v"(t)); return t; }
; __device__ void phase_gemm_qkv(const P& p, int vb, int nvb, char* smem) {
;   const int t = tid_opaque(), kc = t & 7, r0 = t >> 3;
;   const float* Ct = (const float*)smem; const float* rs = (const float*)(smem + LDS_RS);
;   const uint16_t* z = (const uint16_t*)(p.ws + WS_Z);
;   uint16_t* Q = (uint16_t*)(p.ws + WS_Q); uint16_t* Kn = (uint16_t*)(p.ws + WS_KN); uint16_t* Vt = (uint16_t*)(p.ws + WS_VT);
;   const float* cost = (const float*)(p.ws + WS_ROPE); const float* sint = cost + TP * 16;
;   const bool az[4] = {false, false, false, false};
;   for (int tile = vb; tile < 264 * 14; tile += nvb) {
;     const int mt = tile / 14, nt = tile - mt * 14;
;     const char* arow[4];
;     if (nt < 6) {
; #pragma unroll
;       for (int i = 0; i < 4; i++) arow[i] = (const char*)(z + (size_t)(mt * 128 + r0 + 32 * i) * ZW + 1024);
;       gemm_core<0, false, false, 256>(smem, arow, az, (const uint16_t*)(p.ws + WS_WT_UQ), nt * 128, nt);
.LBB0_140:
	s_add_u32 s44, s80, 0x10934000
	s_addc_u32 s45, s81, 0
	s_add_u32 s46, s80, 0x13ab4000
	s_addc_u32 s47, s81, 0
	s_add_u32 s48, s80, 0x15bb4000
	s_addc_u32 s49, s81, 0
	s_cmpk_gt_i32 s2, 0xe6f
	v_mov_b32_e32 v0, v178
	s_cbranch_scc1 .LBB0_223
	v_mbcnt_hi_u32_b32 v162, -1, v179
	v_ashrrev_i32_e32 v160, 3, v0
	s_sub_u32 s0, s82, s2
	s_sub_u32 s0, s0, 1
	s_lshl_b32 s0, s0, 7
	v_and_b32_e32 v0, 64, v162
	s_add_i32 s62, s0, 0xfffffb00
	s_lshl_b32 s63, s82, 7
	s_movk_i32 s50, 0xb00
	v_mov_b32_e32 v153, 0
	s_mov_b64 s[72:73], 0x2000
	s_movk_i32 s51, 0x90
	s_mov_b32 s27, 0
	v_mov_b32_e32 v161, 0x358637bd
	s_mov_b32 s42, 0x800000
	s_movk_i32 s43, 0x210
	s_movk_i32 s34, 0x2100
	s_mov_b32 s35, 0x3e0f83e1
	s_movk_i32 s36, 0x600
	v_xor_b32_e32 v163, 1, v162
	v_add_u32_e32 v164, 64, v0
	v_xor_b32_e32 v165, 2, v162
	v_xor_b32_e32 v166, 4, v162
	s_sub_u32 s37, s82, s2
	s_sub_u32 s37, s37, 1
	s_branch .LBB0_144
